# gdn scan loop: S and v_new LDS fragments read once and reused (4 S reads issued together at step top, qg*S MFMAs before the v_new barrier, second key tile reuses v_new fragments)
# baseline (speedup 1.0000x reference)
; #define LAS __attribute__((address_space(3)))
; __device__ __forceinline__ f32x4 mma16(const h16x8 a, const h16x8 b, const f32x4 c) { return __builtin_amdgcn_mfma_f32_16x16x32_f16(a, b, c, 0, 0, 0); }
; __device__ __forceinline__ void phase_gdn_scan(const int wid_s, CParams& p, LAS unsigned char* lds) {
;     ...
;         for (int n = 0; n < 64; ++n) {
;             const int tc0 = b * SEQ + n * 64;
;             const LAS h16* Sc = St + cur * (32 * 136); LAS h16* Sn = St + (cur ^ 1) * (32 * 136);
;             { const int nn = n + 1 < 64 ? n + 1 : n; SCAN_LOAD(wfn, uun, qfn, infn, kfn, egln, nn); }
;             {
;                 f32x4 acc = {0.f, 0.f, 0.f, 0.f};
; #pragma unroll
;                 for (int ks = 0; ks < 4; ++ks) acc = mma16(*(const LAS h16x8*)(Sc + (16 * vt + lr) * 136 + 32 * ks + 8 * lq), wf[ks], acc);
; #pragma unroll
;                 for (int r = 0; r < 4; ++r) Vnt[(16 * vt + 4 * lq + r) * 72 + 16 * wq + lr] = (h16)((float)uu[r] - acc[r]);
;             }
;             __syncthreads();
;             {
;                 f32x4 acc = {0.f, 0.f, 0.f, 0.f};
; #pragma unroll
;                 for (int ks = 0; ks < 4; ++ks) acc = mma16(qf[ks], *(const LAS h16x8*)(Sc + (16 * vt + lr) * 136 + 32 * ks + 8 * lq), acc);
; #pragma unroll
;                 for (int ks = 0; ks < 2; ++ks) acc = mma16(inf[ks], *(const LAS h16x8*)(Vnt + (16 * vt + lr) * 72 + 32 * ks + 8 * lq), acc);
; #pragma unroll
;                 for (int r = 0; r < 4; ++r) y[(size_t)(tc0 + 16 * wq + 4 * lq + r) * D + 512 + h * 128 + 32 * sl + 16 * vt + lr] = (h16)acc[r];
;             }
; #pragma unroll
;             for (int i = 0; i < 2; ++i) {
;                 f32x4 acc = st[i] * __expf(egl);
; #pragma unroll
;                 for (int ks = 0; ks < 2; ++ks) acc = mma16(*(const LAS h16x8*)(Vnt + (16 * vt + lr) * 72 + 32 * ks + 8 * lq), kf[i][ks], acc);
;                 st[i] = acc;
; #pragma unroll
;                 for (int r = 0; r < 4; ++r) Sn[(16 * vt + 4 * lq + r) * 136 + 16 * (2 * wq + i) + lr] = (h16)acc[r];
;             }
;             __syncthreads();
;             cur ^= 1;
; #pragma unroll
;             for (int ks = 0; ks < 4; ++ks) { wf[ks] = wfn[ks]; qf[ks] = qfn[ks]; }
; #pragma unroll
;             for (int ks = 0; ks < 2; ++ks) { inf[ks] = infn[ks]; kf[0][ks] = kfn[0][ks]; kf[1][ks] = kfn[1][ks]; }
;             uu = uun; egl = egln;
.LBB0_1285:
	v_mov_b64_e32 v[68:69], v[4:5]
	v_mov_b64_e32 v[66:67], v[2:3]
	s_add_i32 s13, s12, 64
	v_add_u32_e32 v2, s12, v161
	v_mov_b64_e32 v[168:169], v[40:41]
	s_add_i32 s19, s13, s6
	v_mad_i64_i32 v[4:5], s[20:21], v2, s86, v[142:143]
	v_mov_b64_e32 v[166:167], v[38:39]
	s_ashr_i32 s22, s19, 4
	global_load_dwordx4 v[62:65], v[4:5], off
	global_load_dwordx4 v[58:61], v[4:5], off offset:64
	global_load_dwordx4 v[54:57], v[4:5], off offset:128
	global_load_dwordx4 v[38:41], v[4:5], off offset:192
	v_mad_i64_i32 v[4:5], s[20:21], v2, s86, v[146:147]
	v_ashrrev_i32_e32 v3, 31, v2
	s_or_b32 s20, s22, s7
	v_lshlrev_b64 v[2:3], 10, v[2:3]
	s_ashr_i32 s21, s20, 31
	v_mov_b64_e32 v[164:165], v[32:33]
	v_lshl_add_u64 v[2:3], v[144:145], 0, v[2:3]
	s_lshl_b64 s[22:23], s[20:21], 13
	v_mov_b64_e32 v[162:163], v[30:31]
	v_mov_b64_e32 v[174:175], v[140:141]
	v_mov_b64_e32 v[88:89], v[36:37]
	v_mov_b64_e32 v[84:85], v[28:29]
	global_load_dwordx2 v[140:141], v[4:5], off offset:1024
	global_load_dwordx4 v[50:53], v[2:3], off
	global_load_dwordx4 v[46:49], v[2:3], off offset:64
	global_load_dwordx4 v[42:45], v[2:3], off offset:128
	global_load_dwordx4 v[30:33], v[2:3], off offset:192
	v_lshl_add_u64 v[2:3], v[130:131], 0, s[22:23]
	s_lshl_b64 s[22:23], s[20:21], 7
	v_mov_b64_e32 v[86:87], v[34:35]
	v_mov_b64_e32 v[82:83], v[26:27]
	global_load_dwordx4 v[34:37], v[2:3], off
	global_load_dwordx4 v[26:29], v[2:3], off offset:64
	v_mov_b32_e32 v3, s23
	v_or_b32_e32 v2, s22, v114
	v_lshl_add_u64 v[4:5], v[2:3], 0, v[120:121]
	v_lshl_add_u64 v[2:3], v[2:3], 0, v[132:133]
	s_mul_i32 s24, s11, 0x2200
	v_lshlrev_b64 v[4:5], 7, v[4:5]
	v_lshlrev_b64 v[2:3], 7, v[2:3]
	v_mov_b64_e32 v[80:81], v[20:21]
	v_mov_b64_e32 v[76:77], v[16:17]
	v_mov_b64_e32 v[72:73], v[8:9]
	v_lshl_add_u64 v[4:5], v[122:123], 0, v[4:5]
	v_lshl_add_u64 v[2:3], v[122:123], 0, v[2:3]
	v_add_u32_e32 v135, s24, v117
	v_mov_b64_e32 v[78:79], v[18:19]
	v_mov_b64_e32 v[74:75], v[14:15]
	v_mov_b64_e32 v[70:71], v[6:7]
	global_load_dwordx4 v[18:21], v[4:5], off
	global_load_dwordx4 v[14:17], v[4:5], off offset:64
	global_load_dwordx4 v[6:9], v[2:3], off
	s_nop 0
	global_load_dwordx4 v[2:5], v[2:3], off offset:64
	ds_read_b128 v[200:203], v135
	ds_read_b128 v[204:207], v135 offset:64
	ds_read_b128 v[208:211], v135 offset:128
	ds_read_b128 v[212:215], v135 offset:192
	s_xor_b32 s11, s11, 1
	s_lshl_b64 s[20:21], s[20:21], 2
	s_add_u32 s20, s15, s20
	s_addc_u32 s21, s16, s21
	v_mov_b32_e32 v137, v154
	global_load_dword v154, v1, s[20:21]
	s_waitcnt lgkmcnt(3)
	v_mfma_f32_16x16x32_f16 v[110:113], v[200:203], v[110:113], 0
	s_waitcnt lgkmcnt(2)
	v_mfma_f32_16x16x32_f16 v[90:93], v[204:207], v[90:93], v[110:113]
	s_waitcnt lgkmcnt(1)
	v_mfma_f32_16x16x32_f16 v[90:93], v[208:211], v[98:101], v[90:93]
	s_waitcnt lgkmcnt(0)
	v_mfma_f32_16x16x32_f16 v[90:93], v[212:215], v[166:169], v[90:93]
	v_mfma_f32_16x16x32_f16 v[184:187], v[94:97], v[200:203], 0
	v_mfma_f32_16x16x32_f16 v[184:187], v[102:105], v[204:207], v[184:187]
	v_mfma_f32_16x16x32_f16 v[184:187], v[106:109], v[208:211], v[184:187]
	v_mfma_f32_16x16x32_f16 v[184:187], v[162:165], v[212:215], v[184:187]
	v_cvt_f32_f16_e32 v98, v174
	s_mul_i32 s19, s11, 0x2200
	s_cmpk_eq_i32 s13, 0xfc0
	s_nop 0
	s_nop 0
	s_nop 2
	v_sub_f32_e32 v90, v98, v90
	v_cvt_f16_f32_e32 v90, v90
	s_nop 0
	s_nop 0
	s_nop 0
	ds_write_b16 v153, v90 offset:17408
	v_cvt_f32_f16_sdwa v90, v174 dst_sel:DWORD dst_unused:UNUSED_PAD src0_sel:WORD_1
	s_nop 0
	s_nop 0
	s_nop 0
	s_nop 0
	v_sub_f32_e32 v90, v90, v91
	v_cvt_f16_f32_e32 v90, v90
	s_nop 0
	ds_write_b16 v153, v90 offset:17552
	v_cvt_f32_f16_e32 v90, v175
	v_sub_f32_e32 v90, v90, v92
	v_cvt_f16_f32_e32 v90, v90
	ds_write_b16 v153, v90 offset:17696
	v_cvt_f32_f16_sdwa v90, v175 dst_sel:DWORD dst_unused:UNUSED_PAD src0_sel:WORD_1
	v_sub_f32_e32 v90, v90, v93
	v_cvt_f16_f32_e32 v90, v90
	ds_write_b16 v153, v90 offset:17840
	s_waitcnt lgkmcnt(0)
	s_barrier
	v_add_u32_e32 v135, v115, v118
	ds_read_b128 v[94:97], v135 offset:17408
	ds_read_b128 v[90:93], v135 offset:17472
	s_waitcnt lgkmcnt(1)
	v_mfma_f32_16x16x32_f16 v[86:89], v[86:89], v[94:97], v[184:187]
	s_waitcnt lgkmcnt(0)
	v_mfma_f32_16x16x32_f16 v[82:85], v[82:85], v[90:93], v[86:89]
	s_nop 2
	v_add_u32_e32 v86, s12, v155
	v_ashrrev_i32_e32 v87, 31, v86
	v_lshlrev_b64 v[88:89], 11, v[86:87]
	s_nop 1
	v_cvt_f16_f32_e32 v82, v82
	v_lshl_add_u64 v[88:89], v[138:139], 0, v[88:89]
	v_cvt_f16_f32_e32 v87, v83
	v_cvt_f16_f32_e32 v84, v84
	global_store_short v[88:89], v82, off
	v_add_u32_e32 v82, 1, v86
	v_ashrrev_i32_e32 v83, 31, v82
	v_lshlrev_b64 v[82:83], 11, v[82:83]
	v_lshl_add_u64 v[82:83], v[138:139], 0, v[82:83]
	global_store_short v[82:83], v87, off
	v_add_u32_e32 v82, 2, v86
	v_ashrrev_i32_e32 v83, 31, v82
	v_lshlrev_b64 v[82:83], 11, v[82:83]
	v_lshl_add_u64 v[82:83], v[138:139], 0, v[82:83]
	global_store_short v[82:83], v84, off
	v_cvt_f16_f32_e32 v84, v85
	v_add_u32_e32 v82, 3, v86
	v_ashrrev_i32_e32 v83, 31, v82
	v_lshlrev_b64 v[82:83], 11, v[82:83]
	v_lshl_add_u64 v[82:83], v[138:139], 0, v[82:83]
	global_store_short v[82:83], v84, off
	v_mul_f32_e32 v82, 0x3fb8aa3b, v137
	v_exp_f32_e32 v82, v82
	s_mov_b32 s12, s13
	s_nop 0
	v_pk_mul_f32 v[24:25], v[24:25], v[82:83] op_sel_hi:[1,0]
	v_pk_mul_f32 v[22:23], v[22:23], v[82:83] op_sel_hi:[1,0]
	v_pk_mul_f32 v[12:13], v[12:13], v[82:83] op_sel_hi:[1,0]
	v_pk_mul_f32 v[10:11], v[10:11], v[82:83] op_sel_hi:[1,0]
	v_mfma_f32_16x16x32_f16 v[22:25], v[94:97], v[78:81], v[22:25]
	v_add3_u32 v78, v148, s19, v149
	s_nop 0
	s_nop 0
	v_mfma_f32_16x16x32_f16 v[22:25], v[90:93], v[74:77], v[22:25]
	v_mfma_f32_16x16x32_f16 v[10:13], v[94:97], v[70:73], v[10:13]
	v_mfma_f32_16x16x32_f16 v[10:13], v[90:93], v[66:69], v[10:13]
	s_nop 0
	s_nop 0
	s_nop 0
	s_nop 0
	s_nop 0
	s_nop 2
	v_cvt_f16_f32_e32 v74, v22
	s_nop 0
	ds_write_b16 v78, v74
	v_cvt_f16_f32_e32 v74, v23
	ds_write_b16 v78, v74 offset:272
	v_cvt_f16_f32_e32 v74, v24
	ds_write_b16 v78, v74 offset:544
	v_cvt_f16_f32_e32 v74, v25
	ds_write_b16 v78, v74 offset:816
	s_nop 7
	v_cvt_f16_f32_e32 v66, v10
	ds_write_b16 v78, v66 offset:32
	v_cvt_f16_f32_e32 v66, v11
	ds_write_b16 v78, v66 offset:304
	v_cvt_f16_f32_e32 v66, v12
	ds_write_b16 v78, v66 offset:576
	v_cvt_f16_f32_e32 v66, v13
	ds_write_b16 v78, v66 offset:848
	s_waitcnt vmcnt(4)
	v_mov_b32_e32 v110, v62
	v_mov_b32_e32 v111, v63
	v_mov_b32_e32 v112, v64
	v_mov_b32_e32 v113, v65
	v_mov_b32_e32 v98, v54
	v_mov_b32_e32 v99, v55
	v_mov_b32_e32 v100, v56
	v_mov_b32_e32 v101, v57
	v_mov_b32_e32 v102, v46
	v_mov_b32_e32 v103, v47
	v_mov_b32_e32 v104, v48
	v_mov_b32_e32 v105, v49
	v_mov_b32_e32 v106, v42
	v_mov_b32_e32 v107, v43
	v_mov_b32_e32 v108, v44
	v_mov_b32_e32 v109, v45
	v_mov_b32_e32 v94, v50
	v_mov_b32_e32 v95, v51
	v_mov_b32_e32 v90, v58
	v_mov_b32_e32 v91, v59
	v_mov_b32_e32 v92, v60
	v_mov_b32_e32 v93, v61
	v_mov_b32_e32 v96, v52
	v_mov_b32_e32 v97, v53
	s_waitcnt lgkmcnt(0)
	s_barrier
; #define LAS __attribute__((address_space(3)))
; __device__ __forceinline__ f32x4 mma16(const h16x8 a, const h16x8 b, const f32x4 c) { return __builtin_amdgcn_mfma_f32_16x16x32_f16(a, b, c, 0, 0, 0); }
; __device__ __forceinline__ void phase_gdn_scan(const int wid_s, CParams& p, LAS unsigned char* lds) {
;     ...
;         for (int n = 0; n < 64; ++n) {
;             const int tc0 = b * SEQ + n * 64;
;             const LAS h16* Sc = St + cur * (32 * 136); LAS h16* Sn = St + (cur ^ 1) * (32 * 136);
;             { const int nn = n + 1 < 64 ? n + 1 : n; SCAN_LOAD(wfn, uun, qfn, infn, kfn, egln, nn); }
;             {
;                 f32x4 acc = {0.f, 0.f, 0.f, 0.f};
; #pragma unroll
;                 for (int ks = 0; ks < 4; ++ks) acc = mma16(*(const LAS h16x8*)(Sc + (16 * vt + lr) * 136 + 32 * ks + 8 * lq), wf[ks], acc);
; #pragma unroll
;                 for (int r = 0; r < 4; ++r) Vnt[(16 * vt + 4 * lq + r) * 72 + 16 * wq + lr] = (h16)((float)uu[r] - acc[r]);
;             }
;             __syncthreads();
;             {
;                 f32x4 acc = {0.f, 0.f, 0.f, 0.f};
; #pragma unroll
;                 for (int ks = 0; ks < 4; ++ks) acc = mma16(qf[ks], *(const LAS h16x8*)(Sc + (16 * vt + lr) * 136 + 32 * ks + 8 * lq), acc);
; #pragma unroll
;                 for (int ks = 0; ks < 2; ++ks) acc = mma16(inf[ks], *(const LAS h16x8*)(Vnt + (16 * vt + lr) * 72 + 32 * ks + 8 * lq), acc);
; #pragma unroll
;                 for (int r = 0; r < 4; ++r) y[(size_t)(tc0 + 16 * wq + 4 * lq + r) * D + 512 + h * 128 + 32 * sl + 16 * vt + lr] = (h16)acc[r];
;             }
; #pragma unroll
;             for (int i = 0; i < 2; ++i) {
;                 f32x4 acc = st[i] * __expf(egl);
; #pragma unroll
;                 for (int ks = 0; ks < 2; ++ks) acc = mma16(*(const LAS h16x8*)(Vnt + (16 * vt + lr) * 72 + 32 * ks + 8 * lq), kf[i][ks], acc);
;                 st[i] = acc;
; #pragma unroll
;                 for (int r = 0; r < 4; ++r) Sn[(16 * vt + 4 * lq + r) * 136 + 16 * (2 * wq + i) + lr] = (h16)acc[r];
;             }
;             __syncthreads();
;             cur ^= 1;
; #pragma unroll
;             for (int ks = 0; ks < 4; ++ks) { wf[ks] = wfn[ks]; qf[ks] = qfn[ks]; }
; #pragma unroll
;             for (int ks = 0; ks < 2; ++ks) { inf[ks] = infn[ks]; kf[0][ks] = kfn[0][ks]; kf[1][ks] = kfn[1][ks]; }
;             uu = uun; egl = egln;
;         }
	s_cbranch_scc0 .LBB0_1285
	ds_read_b128 v[66:69], v117 offset:8704
	v_add_u32_e32 v70, s10, v119
	v_readlane_b32 s6, v253, 0
	s_add_i32 s18, s18, s6
	v_readlane_b32 s6, v253, 57
	s_add_i32 s17, s17, s6
	s_cmpk_gt_i32 s18, 0xff
	s_waitcnt lgkmcnt(0)
	v_mfma_f32_16x16x32_f16 v[62:65], v[66:69], v[62:65], 0
	ds_read_b128 v[66:69], v117 offset:8768
	s_waitcnt lgkmcnt(0)
	v_mfma_f32_16x16x32_f16 v[58:61], v[66:69], v[58:61], v[62:65]
	s_nop 4
	ds_read_b128 v[62:65], v117 offset:8832
	s_waitcnt lgkmcnt(0)
	v_mfma_f32_16x16x32_f16 v[54:57], v[62:65], v[54:57], v[58:61]
	s_nop 2
	ds_read_b128 v[58:61], v117 offset:8896
	s_waitcnt lgkmcnt(0)
	v_mfma_f32_16x16x32_f16 v[38:41], v[58:61], v[38:41], v[54:57]
	s_nop 2
	v_cvt_f32_f16_e32 v54, v140
	s_nop 3
	v_sub_f32_e32 v38, v54, v38
	v_cvt_f16_f32_e32 v38, v38
	ds_write_b16 v153, v38 offset:17408
	v_cvt_f32_f16_sdwa v38, v140 dst_sel:DWORD dst_unused:UNUSED_PAD src0_sel:WORD_1
	v_sub_f32_e32 v38, v38, v39
	v_cvt_f16_f32_e32 v38, v38
	ds_write_b16 v153, v38 offset:17552
	v_cvt_f32_f16_e32 v38, v141
	v_sub_f32_e32 v38, v38, v40
	v_cvt_f16_f32_e32 v38, v38
	ds_write_b16 v153, v38 offset:17696
	v_cvt_f32_f16_sdwa v38, v141 dst_sel:DWORD dst_unused:UNUSED_PAD src0_sel:WORD_1
	v_sub_f32_e32 v38, v38, v41
	v_cvt_f16_f32_e32 v38, v38
	ds_write_b16 v153, v38 offset:17840
	s_waitcnt lgkmcnt(0)
	s_barrier
	ds_read_b128 v[38:41], v117 offset:8704
	s_waitcnt lgkmcnt(0)
	v_mfma_f32_16x16x32_f16 v[38:41], v[50:53], v[38:41], 0
	ds_read_b128 v[50:53], v117 offset:8768
	s_waitcnt lgkmcnt(0)
	v_mfma_f32_16x16x32_f16 v[38:41], v[46:49], v[50:53], v[38:41]
	ds_read_b128 v[46:49], v117 offset:8832
	s_waitcnt lgkmcnt(0)
	v_mfma_f32_16x16x32_f16 v[38:41], v[42:45], v[46:49], v[38:41]
	ds_read_b128 v[42:45], v117 offset:8896
	s_waitcnt vmcnt(11) lgkmcnt(0)
	v_mfma_f32_16x16x32_f16 v[30:33], v[30:33], v[42:45], v[38:41]
	s_nop 4
	ds_read_b128 v[38:41], v135 offset:17408
	s_waitcnt vmcnt(10) lgkmcnt(0)
	v_mfma_f32_16x16x32_f16 v[34:37], v[34:37], v[38:41], v[30:33]
	s_nop 2
	ds_read_b128 v[30:33], v135 offset:17472
	s_waitcnt vmcnt(9) lgkmcnt(0)
	v_mfma_f32_16x16x32_f16 v[26:29], v[26:29], v[30:33], v[34:37]
	s_nop 2
	v_add_u32_e32 v34, 0xfc0, v70
	v_ashrrev_i32_e32 v35, 31, v34
	s_nop 2
	v_cvt_f16_f32_e32 v26, v26
	v_lshlrev_b64 v[34:35], 11, v[34:35]
	v_lshl_add_u64 v[34:35], v[138:139], 0, v[34:35]
	v_cvt_f16_f32_e32 v28, v28
	global_store_short v[34:35], v26, off
	v_cvt_f16_f32_e32 v34, v27
	v_add_u32_e32 v26, 0xfc1, v70
	v_ashrrev_i32_e32 v27, 31, v26
	v_lshlrev_b64 v[26:27], 11, v[26:27]
	v_lshl_add_u64 v[26:27], v[138:139], 0, v[26:27]
	global_store_short v[26:27], v34, off
	v_add_u32_e32 v26, 0xfc2, v70
	v_ashrrev_i32_e32 v27, 31, v26
	v_lshlrev_b64 v[26:27], 11, v[26:27]
	v_lshl_add_u64 v[26:27], v[138:139], 0, v[26:27]
	global_store_short v[26:27], v28, off
	v_cvt_f16_f32_e32 v28, v29
	v_add_u32_e32 v26, 0xfc3, v70
	v_ashrrev_i32_e32 v27, 31, v26
	v_lshlrev_b64 v[26:27], 11, v[26:27]
	v_lshl_add_u64 v[26:27], v[138:139], 0, v[26:27]
	global_store_short v[26:27], v28, off
	s_waitcnt vmcnt(8)
	v_mul_f32_e32 v26, 0x3fb8aa3b, v154
	v_exp_f32_e32 v26, v26
	s_nop 0
	v_pk_mul_f32 v[24:25], v[26:27], v[24:25] op_sel_hi:[0,1]
	v_pk_mul_f32 v[22:23], v[26:27], v[22:23] op_sel_hi:[0,1]
	v_pk_mul_f32 v[12:13], v[26:27], v[12:13] op_sel_hi:[0,1]
	v_pk_mul_f32 v[10:11], v[26:27], v[10:11] op_sel_hi:[0,1]
	v_mfma_f32_16x16x32_f16 v[18:21], v[38:41], v[18:21], v[22:25]
	v_mfma_f32_16x16x32_f16 v[14:17], v[30:33], v[14:17], v[18:21]
	s_nop 6
	v_add_u32_e32 v18, v148, v149
	v_cvt_f16_f32_e32 v14, v14
	ds_write_b16 v18, v14
	v_cvt_f16_f32_e32 v14, v15
	ds_write_b16 v18, v14 offset:272
	v_cvt_f16_f32_e32 v14, v16
	ds_write_b16 v18, v14 offset:544
	v_cvt_f16_f32_e32 v14, v17
	ds_write_b16 v18, v14 offset:816
	ds_read_b128 v[14:17], v135 offset:17408
	s_waitcnt lgkmcnt(0)
	v_mfma_f32_16x16x32_f16 v[6:9], v[14:17], v[6:9], v[10:13]
	s_nop 2
	ds_read_b128 v[10:13], v135 offset:17472
	s_waitcnt lgkmcnt(0)
	v_mfma_f32_16x16x32_f16 v[2:5], v[10:13], v[2:5], v[6:9]
	s_nop 7
	v_cvt_f16_f32_e32 v2, v2
	ds_write_b16 v18, v2 offset:32
	v_cvt_f16_f32_e32 v2, v3
	ds_write_b16 v18, v2 offset:304
	v_cvt_f16_f32_e32 v2, v4
	ds_write_b16 v18, v2 offset:576
	v_cvt_f16_f32_e32 v2, v5
	ds_write_b16 v18, v2 offset:848
	s_waitcnt lgkmcnt(0)
	s_barrier
	s_cbranch_scc0 .LBB0_1281
